# overlap GEMM2 tail round (WGs 0-63) with first part of final RMSNorm phase on WGs 64-255 via counter word + release/acquire; final phase split by row groups
# speedup vs baseline: 1.0374x; 1.0101x over previous
; #define PG8_STAGE(bufoff, gbase, voff) do { _Pragma("unroll") for (int _i = 0; _i < 2; ++_i) \
;         __builtin_amdgcn_global_load_lds((const unsigned*)((const char*)(gbase) + (voff)[_i]), (LAS unsigned*)(lds + (bufoff) + ldsw + _i * 8192), 16, 0, 0); } while (0)
; #define PG8_LDA(dst, b, h) do { _Pragma("unroll") for (int m = 0; m < 4; ++m) _Pragma("unroll") for (int k = 0; k < 2; ++k) dst[m][k] = *(const LAS bf16x8*)(lds + PG8_SA(b, h) + aoff + m * 2048 + k * 1024); } while (0)
; #define PG8_LDB(dst, b, h) do { _Pragma("unroll") for (int n = 0; n < 2; ++n) _Pragma("unroll") for (int k = 0; k < 2; ++k) dst[n][k] = *(const LAS bf16x8*)(lds + PG8_SB(b, h) + boff + n * 2048 + k * 1024); } while (0)
; #define PG8_MMA(ai, bj, At, Bt) do { __builtin_amdgcn_s_setprio(1); _Pragma("unroll") for (int m = 0; m < 4; ++m) _Pragma("unroll") for (int n = 0; n < 2; ++n) _Pragma("unroll") for (int k = 0; k < 2; ++k) \
;         acc[ai][bj][m][n] = __builtin_amdgcn_mfma_f32_16x16x32_bf16(Bt[n][k], At[m][k], acc[ai][bj][m][n], 0, 0, 0); __builtin_amdgcn_s_setprio(0); } while (0)
; #define PG8_WAIT_L(n) asm volatile("s_waitcnt lgkmcnt(" #n ")" ::: "memory")
; #define PG8_BAR __builtin_amdgcn_s_barrier()
; #define PG8_SCHED __builtin_amdgcn_sched_barrier(0)
; template <class Epi>
; __device__ __forceinline__ void gemm_phase(LAS unsigned char* lds, const Gemm g, const StaticOrder& S, const Epi& E) {
;     ...
;             PG8_LDB(B0, 0, 0); PG8_SCHED; PG8_LDA(At, 0, 0); PG8_STAGE(PG8_SA(1, 1), a1 + hstep, voffA);
;             PG8_WAIT_L(8); PG8_BAR; PG8_WAIT_L(0); PG8_MMA(0, 0, At, B0); PG8_BAR; PG8_SCHED;
;             PG8_LDB(B1, 0, 1); PG8_STAGE(PG8_SB(0, 0), b2, voffB);
;             PG8_BAR; PG8_WAIT_L(0); PG8_MMA(0, 1, At, B1); PG8_BAR;
;             PG8_LDA(At, 0, 1); PG8_STAGE(PG8_SA(0, 0), a2, voffA);
;             PG8_BAR; PG8_WAIT_L(0); PG8_MMA(1, 0, At, B0); PG8_BAR; PG8_SCHED;
.LBB0_559:
	ds_read_b128 v[156:159], v133
	ds_read_b128 v[160:163], v133 offset:1024
	ds_read_b128 v[164:167], v133 offset:2048
	ds_read_b128 v[168:171], v133 offset:3072
	s_add_u32 s34, s30, 0xfff80080
	s_addc_u32 s35, s31, -1
	s_cmp_eq_u32 s65, 28
	s_cselect_b32 s41, s25, s35
	s_cselect_b32 s40, s61, s34
	s_cselect_b32 s35, s23, s64
	s_cselect_b32 s34, s62, s63
	v_lshl_add_u64 v[204:205], s[30:31], 0, v[142:143]
	s_add_i32 m0, s21, 0xc000
	ds_read_b128 v[172:175], v153
	ds_read_b128 v[176:179], v153 offset:1024
	ds_read_b128 v[180:183], v153 offset:2048
	ds_read_b128 v[184:187], v153 offset:3072
	ds_read_b128 v[188:191], v153 offset:4096
	ds_read_b128 v[192:195], v153 offset:5120
	ds_read_b128 v[196:199], v153 offset:6144
	ds_read_b128 v[200:203], v153 offset:7168
	global_load_lds_dwordx4 v[204:205], off
	v_lshl_add_u64 v[204:205], s[30:31], 0, v[144:145]
	s_add_i32 m0, s21, 0xe000
	s_nop 0
	global_load_lds_dwordx4 v[204:205], off
	s_waitcnt lgkmcnt(8)
	s_barrier
	s_waitcnt lgkmcnt(0)
	s_setprio 1
	s_waitcnt lgkmcnt(0)
	v_mfma_f32_16x16x32_bf16 v[124:127], v[156:159], v[172:175], v[124:127]
	v_mfma_f32_16x16x32_bf16 v[120:123], v[164:167], v[172:175], v[120:123]
	v_mfma_f32_16x16x32_bf16 v[116:119], v[156:159], v[180:183], v[116:119]
	v_mfma_f32_16x16x32_bf16 v[112:115], v[164:167], v[180:183], v[112:115]
	v_mfma_f32_16x16x32_bf16 v[100:103], v[156:159], v[188:191], v[100:103]
	v_mfma_f32_16x16x32_bf16 v[96:99], v[164:167], v[188:191], v[96:99]
	v_mfma_f32_16x16x32_bf16 v[84:87], v[156:159], v[196:199], v[84:87]
	v_mfma_f32_16x16x32_bf16 v[80:83], v[164:167], v[196:199], v[80:83]
	v_mfma_f32_16x16x32_bf16 v[124:127], v[160:163], v[176:179], v[124:127]
	v_mfma_f32_16x16x32_bf16 v[120:123], v[168:171], v[176:179], v[120:123]
	v_mfma_f32_16x16x32_bf16 v[116:119], v[160:163], v[184:187], v[116:119]
	v_mfma_f32_16x16x32_bf16 v[112:115], v[168:171], v[184:187], v[112:115]
	v_mfma_f32_16x16x32_bf16 v[100:103], v[160:163], v[192:195], v[100:103]
	v_mfma_f32_16x16x32_bf16 v[96:99], v[168:171], v[192:195], v[96:99]
	v_mfma_f32_16x16x32_bf16 v[84:87], v[160:163], v[200:203], v[84:87]
	v_mfma_f32_16x16x32_bf16 v[80:83], v[168:171], v[200:203], v[80:83]
	s_setprio 0
	s_barrier
	s_add_i32 s66, s54, s43
	v_lshl_add_u64 v[220:221], s[34:35], 0, v[138:139]
	s_mov_b32 m0, s66
	ds_read_b128 v[204:207], v154
	ds_read_b128 v[208:211], v154 offset:1024
	ds_read_b128 v[212:215], v154 offset:2048
	ds_read_b128 v[216:219], v154 offset:3072
	global_load_lds_dwordx4 v[220:221], off
	v_lshl_add_u64 v[222:223], s[34:35], 0, v[134:135]
	s_add_i32 m0, s66, 0x2000
	s_nop 0
	global_load_lds_dwordx4 v[222:223], off
	s_barrier
	s_waitcnt lgkmcnt(0)
	s_setprio 1
	s_waitcnt lgkmcnt(0)
	v_mfma_f32_16x16x32_bf16 v[108:111], v[204:207], v[172:175], v[108:111]
	v_mfma_f32_16x16x32_bf16 v[104:107], v[212:215], v[172:175], v[104:107]
	v_mfma_f32_16x16x32_bf16 v[92:95], v[204:207], v[180:183], v[92:95]
	v_mfma_f32_16x16x32_bf16 v[88:91], v[212:215], v[180:183], v[88:91]
	v_mfma_f32_16x16x32_bf16 v[76:79], v[204:207], v[188:191], v[76:79]
	v_mfma_f32_16x16x32_bf16 v[72:75], v[212:215], v[188:191], v[72:75]
	v_mfma_f32_16x16x32_bf16 v[68:71], v[204:207], v[196:199], v[68:71]
	v_mfma_f32_16x16x32_bf16 v[64:67], v[212:215], v[196:199], v[64:67]
	v_mfma_f32_16x16x32_bf16 v[108:111], v[208:211], v[176:179], v[108:111]
	v_mfma_f32_16x16x32_bf16 v[104:107], v[216:219], v[176:179], v[104:107]
	v_mfma_f32_16x16x32_bf16 v[92:95], v[208:211], v[184:187], v[92:95]
	v_mfma_f32_16x16x32_bf16 v[88:91], v[216:219], v[184:187], v[88:91]
	v_mfma_f32_16x16x32_bf16 v[76:79], v[208:211], v[192:195], v[76:79]
	v_mfma_f32_16x16x32_bf16 v[72:75], v[216:219], v[192:195], v[72:75]
	v_mfma_f32_16x16x32_bf16 v[68:71], v[208:211], v[200:203], v[68:71]
	v_mfma_f32_16x16x32_bf16 v[64:67], v[216:219], v[200:203], v[64:67]
	s_setprio 0
	s_mov_b32 m0, s21
	v_lshl_add_u64 v[224:225], s[40:41], 0, v[140:141]
	s_barrier
	ds_read_b128 v[172:175], v153 offset:16384
	ds_read_b128 v[176:179], v153 offset:17408
	ds_read_b128 v[180:183], v153 offset:18432
	ds_read_b128 v[184:187], v153 offset:19456
	ds_read_b128 v[188:191], v153 offset:20480
	ds_read_b128 v[192:195], v153 offset:21504
	ds_read_b128 v[196:199], v153 offset:22528
	ds_read_b128 v[200:203], v153 offset:23552
	global_load_lds_dwordx4 v[224:225], off
	v_lshl_add_u64 v[226:227], s[40:41], 0, v[136:137]
	s_mov_b32 m0, s46
	s_nop 0
	global_load_lds_dwordx4 v[226:227], off
	s_barrier
	s_waitcnt lgkmcnt(0)
	s_setprio 1
	s_waitcnt lgkmcnt(0)
	v_mfma_f32_16x16x32_bf16 v[60:63], v[156:159], v[172:175], v[60:63]
	v_mfma_f32_16x16x32_bf16 v[56:59], v[164:167], v[172:175], v[56:59]
	v_mfma_f32_16x16x32_bf16 v[52:55], v[156:159], v[180:183], v[52:55]
	v_mfma_f32_16x16x32_bf16 v[48:51], v[164:167], v[180:183], v[48:51]
	v_mfma_f32_16x16x32_bf16 v[36:39], v[156:159], v[188:191], v[36:39]
	v_mfma_f32_16x16x32_bf16 v[32:35], v[164:167], v[188:191], v[32:35]
	v_mfma_f32_16x16x32_bf16 v[20:23], v[156:159], v[196:199], v[20:23]
	v_mfma_f32_16x16x32_bf16 v[16:19], v[164:167], v[196:199], v[16:19]
	v_mfma_f32_16x16x32_bf16 v[60:63], v[160:163], v[176:179], v[60:63]
	v_mfma_f32_16x16x32_bf16 v[56:59], v[168:171], v[176:179], v[56:59]
	v_mfma_f32_16x16x32_bf16 v[52:55], v[160:163], v[184:187], v[52:55]
	v_mfma_f32_16x16x32_bf16 v[48:51], v[168:171], v[184:187], v[48:51]
	v_mfma_f32_16x16x32_bf16 v[36:39], v[160:163], v[192:195], v[36:39]
	v_mfma_f32_16x16x32_bf16 v[32:35], v[168:171], v[192:195], v[32:35]
	v_mfma_f32_16x16x32_bf16 v[20:23], v[160:163], v[200:203], v[20:23]
	v_mfma_f32_16x16x32_bf16 v[16:19], v[168:171], v[200:203], v[16:19]
	s_setprio 0
	s_barrier
; #define PG8_STAGE(bufoff, gbase, voff) do { _Pragma("unroll") for (int _i = 0; _i < 2; ++_i) \
;         __builtin_amdgcn_global_load_lds((const unsigned*)((const char*)(gbase) + (voff)[_i]), (LAS unsigned*)(lds + (bufoff) + ldsw + _i * 8192), 16, 0, 0); } while (0)
; #define PG8_LDA(dst, b, h) do { _Pragma("unroll") for (int m = 0; m < 4; ++m) _Pragma("unroll") for (int k = 0; k < 2; ++k) dst[m][k] = *(const LAS bf16x8*)(lds + PG8_SA(b, h) + aoff + m * 2048 + k * 1024); } while (0)
; #define PG8_LDB(dst, b, h) do { _Pragma("unroll") for (int n = 0; n < 2; ++n) _Pragma("unroll") for (int k = 0; k < 2; ++k) dst[n][k] = *(const LAS bf16x8*)(lds + PG8_SB(b, h) + boff + n * 2048 + k * 1024); } while (0)
; #define PG8_MMA(ai, bj, At, Bt) do { __builtin_amdgcn_s_setprio(1); _Pragma("unroll") for (int m = 0; m < 4; ++m) _Pragma("unroll") for (int n = 0; n < 2; ++n) _Pragma("unroll") for (int k = 0; k < 2; ++k) \
;         acc[ai][bj][m][n] = __builtin_amdgcn_mfma_f32_16x16x32_bf16(Bt[n][k], At[m][k], acc[ai][bj][m][n], 0, 0, 0); __builtin_amdgcn_s_setprio(0); } while (0)
; #define PG8_WAIT_V(n) asm volatile("s_waitcnt vmcnt(" #n ")" ::: "memory")
; #define PG8_WAIT_L(n) asm volatile("s_waitcnt lgkmcnt(" #n ")" ::: "memory")
; #define PG8_BAR __builtin_amdgcn_s_barrier()
; #define PG8_SCHED __builtin_amdgcn_sched_barrier(0)
; template <class Epi>
; __device__ __forceinline__ void gemm_phase(LAS unsigned char* lds, const Gemm g, const StaticOrder& S, const Epi& E) {
;     ...
;             PG8_STAGE(PG8_SB(0, 1), b2 + hstep, voffB);
;             PG8_WAIT_V(6); PG8_BAR; PG8_MMA(1, 1, At, B1); PG8_BAR;
;             PG8_LDB(B0, 1, 0); PG8_SCHED; PG8_LDA(At, 1, 0); PG8_STAGE(PG8_SA(0, 1), a2 + hstep, voffA);
;             PG8_WAIT_L(8); PG8_BAR; PG8_WAIT_L(0); PG8_MMA(0, 0, At, B0); PG8_BAR; PG8_SCHED;
;             PG8_LDB(B1, 1, 1); PG8_STAGE(PG8_SB(1, 0), b3, voffB);
;             PG8_BAR; PG8_WAIT_L(0); PG8_MMA(0, 1, At, B1); PG8_BAR;
;             PG8_LDA(At, 1, 1); PG8_STAGE(PG8_SA(1, 0), a3, voffA);
	s_add_u32 s66, s34, 0x80000
	s_addc_u32 s67, s35, 0
	s_add_i32 s68, s55, s43
	v_lshl_add_u64 v[156:157], s[66:67], 0, v[138:139]
	s_mov_b32 m0, s68
	s_nop 0
	global_load_lds_dwordx4 v[156:157], off
	v_lshl_add_u64 v[156:157], s[66:67], 0, v[134:135]
	s_add_i32 m0, s68, 0x2000
	s_nop 0
	global_load_lds_dwordx4 v[156:157], off
	s_waitcnt vmcnt(6)
	s_barrier
	s_setprio 1
	v_mfma_f32_16x16x32_bf16 v[44:47], v[204:207], v[172:175], v[44:47]
	v_mfma_f32_16x16x32_bf16 v[40:43], v[212:215], v[172:175], v[40:43]
	v_mfma_f32_16x16x32_bf16 v[28:31], v[204:207], v[180:183], v[28:31]
	v_mfma_f32_16x16x32_bf16 v[24:27], v[212:215], v[180:183], v[24:27]
	v_mfma_f32_16x16x32_bf16 v[12:15], v[204:207], v[188:191], v[12:15]
	v_mfma_f32_16x16x32_bf16 v[8:11], v[212:215], v[188:191], v[8:11]
	v_mfma_f32_16x16x32_bf16 v[4:7], v[204:207], v[196:199], v[4:7]
	v_mfma_f32_16x16x32_bf16 v[0:3], v[212:215], v[196:199], v[0:3]
	v_mfma_f32_16x16x32_bf16 v[44:47], v[208:211], v[176:179], v[44:47]
	v_mfma_f32_16x16x32_bf16 v[40:43], v[216:219], v[176:179], v[40:43]
	v_mfma_f32_16x16x32_bf16 v[28:31], v[208:211], v[184:187], v[28:31]
	v_mfma_f32_16x16x32_bf16 v[24:27], v[216:219], v[184:187], v[24:27]
	v_mfma_f32_16x16x32_bf16 v[12:15], v[208:211], v[192:195], v[12:15]
	v_mfma_f32_16x16x32_bf16 v[8:11], v[216:219], v[192:195], v[8:11]
	v_mfma_f32_16x16x32_bf16 v[4:7], v[208:211], v[200:203], v[4:7]
	v_mfma_f32_16x16x32_bf16 v[0:3], v[216:219], v[200:203], v[0:3]
	s_setprio 0
	s_add_i32 s66, 0, 0x18000
	v_add_u32_e32 v155, s66, v151
	s_barrier
	ds_read_b128 v[156:159], v155
	ds_read_b128 v[160:163], v155 offset:1024
	ds_read_b128 v[164:167], v155 offset:2048
	ds_read_b128 v[168:171], v155 offset:3072
	s_add_u32 s40, s40, 0x80000
	s_addc_u32 s41, s41, 0
	s_mov_b32 m0, s47
	v_lshl_add_u64 v[204:205], s[40:41], 0, v[140:141]
	ds_read_b128 v[172:175], v153 offset:32768
	ds_read_b128 v[176:179], v153 offset:33792
	ds_read_b128 v[180:183], v153 offset:34816
	ds_read_b128 v[184:187], v153 offset:35840
	ds_read_b128 v[188:191], v153 offset:36864
	ds_read_b128 v[192:195], v153 offset:37888
	ds_read_b128 v[196:199], v153 offset:38912
	ds_read_b128 v[200:203], v153 offset:39936
	global_load_lds_dwordx4 v[204:205], off
	v_lshl_add_u64 v[204:205], s[40:41], 0, v[136:137]
	s_mov_b32 m0, s48
	s_nop 0
	global_load_lds_dwordx4 v[204:205], off
	s_waitcnt lgkmcnt(8)
	s_barrier
	s_waitcnt lgkmcnt(0)
	s_setprio 1
	s_waitcnt lgkmcnt(0)
	v_mfma_f32_16x16x32_bf16 v[124:127], v[156:159], v[172:175], v[124:127]
	v_mfma_f32_16x16x32_bf16 v[120:123], v[164:167], v[172:175], v[120:123]
	v_mfma_f32_16x16x32_bf16 v[116:119], v[156:159], v[180:183], v[116:119]
	v_mfma_f32_16x16x32_bf16 v[112:115], v[164:167], v[180:183], v[112:115]
	v_mfma_f32_16x16x32_bf16 v[100:103], v[156:159], v[188:191], v[100:103]
	v_mfma_f32_16x16x32_bf16 v[96:99], v[164:167], v[188:191], v[96:99]
	v_mfma_f32_16x16x32_bf16 v[84:87], v[156:159], v[196:199], v[84:87]
	v_mfma_f32_16x16x32_bf16 v[80:83], v[164:167], v[196:199], v[80:83]
	v_mfma_f32_16x16x32_bf16 v[124:127], v[160:163], v[176:179], v[124:127]
	v_mfma_f32_16x16x32_bf16 v[120:123], v[168:171], v[176:179], v[120:123]
	v_mfma_f32_16x16x32_bf16 v[116:119], v[160:163], v[184:187], v[116:119]
	v_mfma_f32_16x16x32_bf16 v[112:115], v[168:171], v[184:187], v[112:115]
	v_mfma_f32_16x16x32_bf16 v[100:103], v[160:163], v[192:195], v[100:103]
	v_mfma_f32_16x16x32_bf16 v[96:99], v[168:171], v[192:195], v[96:99]
	v_mfma_f32_16x16x32_bf16 v[84:87], v[160:163], v[200:203], v[84:87]
	v_mfma_f32_16x16x32_bf16 v[80:83], v[168:171], v[200:203], v[80:83]
	s_setprio 0
	s_barrier
	s_add_i32 s40, 0, 0x1c000
	s_add_i32 s41, s66, s43
	v_add_u32_e32 v155, s40, v151
	v_lshl_add_u64 v[220:221], v[220:221], 0, s[12:13]
	s_mov_b32 m0, s41
	ds_read_b128 v[204:207], v155
	ds_read_b128 v[208:211], v155 offset:1024
	ds_read_b128 v[212:215], v155 offset:2048
	ds_read_b128 v[216:219], v155 offset:3072
	global_load_lds_dwordx4 v[220:221], off
	v_lshl_add_u64 v[220:221], v[222:223], 0, s[12:13]
	s_add_i32 m0, s41, 0x2000
	s_nop 0
	global_load_lds_dwordx4 v[220:221], off
	s_barrier
	s_waitcnt lgkmcnt(0)
	s_setprio 1
	s_waitcnt lgkmcnt(0)
	v_mfma_f32_16x16x32_bf16 v[108:111], v[204:207], v[172:175], v[108:111]
	v_mfma_f32_16x16x32_bf16 v[104:107], v[212:215], v[172:175], v[104:107]
	v_mfma_f32_16x16x32_bf16 v[92:95], v[204:207], v[180:183], v[92:95]
	v_mfma_f32_16x16x32_bf16 v[88:91], v[212:215], v[180:183], v[88:91]
	v_mfma_f32_16x16x32_bf16 v[76:79], v[204:207], v[188:191], v[76:79]
	v_mfma_f32_16x16x32_bf16 v[72:75], v[212:215], v[188:191], v[72:75]
	v_mfma_f32_16x16x32_bf16 v[68:71], v[204:207], v[196:199], v[68:71]
	v_mfma_f32_16x16x32_bf16 v[64:67], v[212:215], v[196:199], v[64:67]
	v_mfma_f32_16x16x32_bf16 v[108:111], v[208:211], v[176:179], v[108:111]
	v_mfma_f32_16x16x32_bf16 v[104:107], v[216:219], v[176:179], v[104:107]
	v_mfma_f32_16x16x32_bf16 v[92:95], v[208:211], v[184:187], v[92:95]
	v_mfma_f32_16x16x32_bf16 v[88:91], v[216:219], v[184:187], v[88:91]
	v_mfma_f32_16x16x32_bf16 v[76:79], v[208:211], v[192:195], v[76:79]
	v_mfma_f32_16x16x32_bf16 v[72:75], v[216:219], v[192:195], v[72:75]
	v_mfma_f32_16x16x32_bf16 v[68:71], v[208:211], v[200:203], v[68:71]
	v_mfma_f32_16x16x32_bf16 v[64:67], v[216:219], v[200:203], v[64:67]
	s_setprio 0
	s_mov_b32 m0, s50
	v_lshl_add_u64 v[220:221], v[224:225], 0, s[12:13]
	s_barrier
	ds_read_b128 v[172:175], v153 offset:49152
	ds_read_b128 v[176:179], v153 offset:50176
	ds_read_b128 v[180:183], v153 offset:51200
	ds_read_b128 v[184:187], v153 offset:52224
	ds_read_b128 v[188:191], v153 offset:53248
	ds_read_b128 v[192:195], v153 offset:54272
	ds_read_b128 v[196:199], v153 offset:55296
	ds_read_b128 v[200:203], v153 offset:56320
	global_load_lds_dwordx4 v[220:221], off
	v_lshl_add_u64 v[220:221], v[226:227], 0, s[12:13]
	s_mov_b32 m0, s51
	s_nop 0
	global_load_lds_dwordx4 v[220:221], off
	s_barrier
; __device__ __forceinline__ unsigned pk_bf16(float lo, float hi) { const f32x2 v = (f32x2){lo, hi}; const bf16v2 b = __builtin_convertvector(v, bf16v2); return __builtin_bit_cast(unsigned, b); }
; #define PG8_STAGE(bufoff, gbase, voff) do { _Pragma("unroll") for (int _i = 0; _i < 2; ++_i) \
;         __builtin_amdgcn_global_load_lds((const unsigned*)((const char*)(gbase) + (voff)[_i]), (LAS unsigned*)(lds + (bufoff) + ldsw + _i * 8192), 16, 0, 0); } while (0)
; #define PG8_MMA(ai, bj, At, Bt) do { __builtin_amdgcn_s_setprio(1); _Pragma("unroll") for (int m = 0; m < 4; ++m) _Pragma("unroll") for (int n = 0; n < 2; ++n) _Pragma("unroll") for (int k = 0; k < 2; ++k) \
;         acc[ai][bj][m][n] = __builtin_amdgcn_mfma_f32_16x16x32_bf16(Bt[n][k], At[m][k], acc[ai][bj][m][n], 0, 0, 0); __builtin_amdgcn_s_setprio(0); } while (0)
; #define PG8_WAIT_V(n) asm volatile("s_waitcnt vmcnt(" #n ")" ::: "memory")
; #define PG8_WAIT_L(n) asm volatile("s_waitcnt lgkmcnt(" #n ")" ::: "memory")
; #define PG8_BAR __builtin_amdgcn_s_barrier()
; #define PG8_SCHED __builtin_amdgcn_sched_barrier(0)
; template <class Epi>
; __device__ __forceinline__ void gemm_phase(LAS unsigned char* lds, const Gemm g, const StaticOrder& S, const Epi& E) {
;     ...
;             PG8_BAR; PG8_WAIT_L(0); PG8_MMA(1, 0, At, B0); PG8_BAR; PG8_SCHED;
;             PG8_STAGE(PG8_SB(1, 1), b3 + hstep, voffB);
;             PG8_WAIT_V(6); PG8_BAR; PG8_MMA(1, 1, At, B1); PG8_BAR;
;     __device__ __forceinline__ void operator()(const f32x4 (&acc)[2][2][4][2], const pg8::Unit& u, int wr, int wc, int fr, int fq) const {
;         const int row0 = u.pm * 256 + wr * 64 + fr, col0 = u.pn * 256 + wc * 32 + 8 * fq;
; #pragma unroll
;         for (int ai = 0; ai < 2; ++ai)
; #pragma unroll
;             for (int m = 0; m < 4; ++m) {
;                 const int row = row0 + ai * 128 + m * 16;
;                 bf16_t* orow = yb + (size_t)row * DM + col0;
; #pragma unroll
;                 for (int bj = 0; bj < 2; ++bj) {
;                     const f32x4 v0 = acc[ai][bj][m][0], v1 = acc[ai][bj][m][1];
;                     *(u32x4*)(orow + bj * 128) = (u32x4){pk_bf16(v0[0], v0[1]), pk_bf16(v0[2], v0[3]), pk_bf16(v1[0], v1[1]), pk_bf16(v1[2], v1[3])};
;                 }
	s_waitcnt lgkmcnt(0)
	s_setprio 1
	s_waitcnt lgkmcnt(0)
	v_mfma_f32_16x16x32_bf16 v[60:63], v[156:159], v[172:175], v[60:63]
	v_mfma_f32_16x16x32_bf16 v[56:59], v[164:167], v[172:175], v[56:59]
	v_mfma_f32_16x16x32_bf16 v[52:55], v[156:159], v[180:183], v[52:55]
	v_mfma_f32_16x16x32_bf16 v[48:51], v[164:167], v[180:183], v[48:51]
	v_mfma_f32_16x16x32_bf16 v[36:39], v[156:159], v[188:191], v[36:39]
	v_mfma_f32_16x16x32_bf16 v[32:35], v[164:167], v[188:191], v[32:35]
	v_mfma_f32_16x16x32_bf16 v[20:23], v[156:159], v[196:199], v[20:23]
	v_mfma_f32_16x16x32_bf16 v[16:19], v[164:167], v[196:199], v[16:19]
	v_mfma_f32_16x16x32_bf16 v[60:63], v[160:163], v[176:179], v[60:63]
	v_mfma_f32_16x16x32_bf16 v[56:59], v[168:171], v[176:179], v[56:59]
	v_mfma_f32_16x16x32_bf16 v[52:55], v[160:163], v[184:187], v[52:55]
	v_mfma_f32_16x16x32_bf16 v[48:51], v[168:171], v[184:187], v[48:51]
	v_mfma_f32_16x16x32_bf16 v[36:39], v[160:163], v[192:195], v[36:39]
	v_mfma_f32_16x16x32_bf16 v[32:35], v[168:171], v[192:195], v[32:35]
	v_mfma_f32_16x16x32_bf16 v[20:23], v[160:163], v[200:203], v[20:23]
	v_mfma_f32_16x16x32_bf16 v[16:19], v[168:171], v[200:203], v[16:19]
	s_setprio 0
	s_barrier
	s_add_u32 s34, s34, 0x80080
	s_addc_u32 s35, s35, 0
	s_add_i32 s40, s40, s43
	v_lshl_add_u64 v[156:157], s[34:35], 0, v[138:139]
	s_mov_b32 m0, s40
	s_nop 0
	global_load_lds_dwordx4 v[156:157], off
	v_lshl_add_u64 v[156:157], s[34:35], 0, v[134:135]
	s_add_i32 m0, s40, 0x2000
	s_nop 0
	global_load_lds_dwordx4 v[156:157], off
	s_waitcnt vmcnt(6)
	s_barrier
	s_setprio 1
	v_mfma_f32_16x16x32_bf16 v[44:47], v[204:207], v[172:175], v[44:47]
	v_mfma_f32_16x16x32_bf16 v[40:43], v[212:215], v[172:175], v[40:43]
	v_mfma_f32_16x16x32_bf16 v[28:31], v[204:207], v[180:183], v[28:31]
	v_mfma_f32_16x16x32_bf16 v[24:27], v[212:215], v[180:183], v[24:27]
	v_mfma_f32_16x16x32_bf16 v[12:15], v[204:207], v[188:191], v[12:15]
	v_mfma_f32_16x16x32_bf16 v[8:11], v[212:215], v[188:191], v[8:11]
	v_mfma_f32_16x16x32_bf16 v[4:7], v[204:207], v[196:199], v[4:7]
	v_mfma_f32_16x16x32_bf16 v[0:3], v[212:215], v[196:199], v[0:3]
	v_mfma_f32_16x16x32_bf16 v[44:47], v[208:211], v[176:179], v[44:47]
	v_mfma_f32_16x16x32_bf16 v[40:43], v[216:219], v[176:179], v[40:43]
	v_mfma_f32_16x16x32_bf16 v[28:31], v[208:211], v[184:187], v[28:31]
	v_mfma_f32_16x16x32_bf16 v[24:27], v[216:219], v[184:187], v[24:27]
	v_mfma_f32_16x16x32_bf16 v[12:15], v[208:211], v[192:195], v[12:15]
	v_mfma_f32_16x16x32_bf16 v[8:11], v[216:219], v[192:195], v[8:11]
	v_mfma_f32_16x16x32_bf16 v[4:7], v[208:211], v[200:203], v[4:7]
	v_mfma_f32_16x16x32_bf16 v[0:3], v[216:219], v[200:203], v[0:3]
	s_setprio 0
	s_add_i32 s65, s65, 2
	s_add_u32 s30, s30, 0x100
	s_addc_u32 s31, s31, 0
	s_add_u32 s63, s63, 0x100
	s_addc_u32 s64, s64, 0
	s_cmp_gt_u32 s65, 29
	s_barrier
	s_cbranch_scc0 .LBB0_559
	v_lshl_add_u32 v156, s20, 8, v150
	v_lshl_or_b32 v158, s60, 8, v152
	v_ashrrev_i32_e32 v157, 31, v156
	v_ashrrev_i32_e32 v159, 31, v158
	v_lshlrev_b64 v[160:161], 12, v[156:157]
	v_lshl_add_u64 v[160:161], s[6:7], 0, v[160:161]
	v_lshlrev_b64 v[158:159], 1, v[158:159]
	v_lshl_add_u64 v[160:161], v[160:161], 0, v[158:159]
	v_cvt_pk_bf16_f32 v60, v60, v61
	v_cvt_pk_bf16_f32 v61, v62, v63
	v_cvt_pk_bf16_f32 v62, v56, v57
	v_add_co_u32_e32 v56, vcc, s56, v160
	v_cvt_pk_bf16_f32 v68, v68, v69
	v_cvt_pk_bf16_f32 v69, v70, v71
	v_cvt_pk_bf16_f32 v70, v64, v65
	v_lshl_add_u64 v[64:65], v[160:161], 0, s[10:11]
	v_addc_co_u32_e32 v57, vcc, 0, v161, vcc
	v_cvt_pk_bf16_f32 v44, v44, v45
	v_cvt_pk_bf16_f32 v45, v46, v47
	v_cvt_pk_bf16_f32 v46, v40, v41
	v_cvt_pk_bf16_f32 v47, v42, v43
	v_cvt_pk_bf16_f32 v108, v108, v109
	v_cvt_pk_bf16_f32 v109, v110, v111
	v_cvt_pk_bf16_f32 v110, v104, v105
	v_or_b32_e32 v104, 16, v156
	global_store_dwordx4 v[64:65], v[44:47], off offset:256
	v_ashrrev_i32_e32 v105, 31, v104
	v_cvt_pk_bf16_f32 v92, v92, v93
	v_add_co_u32_e32 v46, vcc, s57, v160
	v_cvt_pk_bf16_f32 v93, v94, v95
	v_cvt_pk_bf16_f32 v94, v88, v89
	v_or_b32_e32 v88, 32, v156
	v_lshl_add_u64 v[44:45], v[160:161], 0, s[14:15]
	v_addc_co_u32_e32 v47, vcc, 0, v161, vcc
	v_cvt_pk_bf16_f32 v28, v28, v29
	v_cvt_pk_bf16_f32 v29, v30, v31
	v_cvt_pk_bf16_f32 v30, v24, v25
	v_cvt_pk_bf16_f32 v31, v26, v27
	v_lshlrev_b64 v[104:105], 12, v[104:105]
	v_ashrrev_i32_e32 v89, 31, v88
	v_cvt_pk_bf16_f32 v76, v76, v77
	v_cvt_pk_bf16_f32 v77, v78, v79
	v_cvt_pk_bf16_f32 v78, v72, v73
	v_or_b32_e32 v72, 48, v156
	global_store_dwordx4 v[44:45], v[28:31], off offset:256
	v_cvt_pk_bf16_f32 v111, v106, v107
	v_lshl_add_u64 v[104:105], s[6:7], 0, v[104:105]
	v_add_co_u32_e32 v30, vcc, s58, v160
	v_lshlrev_b64 v[88:89], 12, v[88:89]
	v_ashrrev_i32_e32 v73, 31, v72
	v_lshl_add_u64 v[28:29], v[160:161], 0, s[16:17]
	v_addc_co_u32_e32 v31, vcc, 0, v161, vcc
	v_cvt_pk_bf16_f32 v12, v12, v13
	v_cvt_pk_bf16_f32 v13, v14, v15
	v_cvt_pk_bf16_f32 v14, v8, v9
	v_cvt_pk_bf16_f32 v15, v10, v11
	global_store_dwordx4 v[160:161], v[108:111], off offset:256
	v_cvt_pk_bf16_f32 v95, v90, v91
	v_lshl_add_u64 v[88:89], s[6:7], 0, v[88:89]
	v_lshl_add_u64 v[108:109], v[104:105], 0, v[158:159]
	v_lshlrev_b64 v[72:73], 12, v[72:73]
	global_store_dwordx4 v[28:29], v[12:15], off offset:256
	global_store_dwordx4 v[108:109], v[92:95], off offset:256
	v_cvt_pk_bf16_f32 v79, v74, v75
	v_add_co_u32_e32 v14, vcc, s59, v160
	v_lshl_add_u64 v[92:93], v[88:89], 0, v[158:159]
	v_lshl_add_u64 v[72:73], s[6:7], 0, v[72:73]
	v_addc_co_u32_e32 v15, vcc, 0, v161, vcc
	v_cvt_pk_bf16_f32 v124, v124, v125
	v_cvt_pk_bf16_f32 v125, v126, v127
	v_cvt_pk_bf16_f32 v126, v120, v121
	v_cvt_pk_bf16_f32 v127, v122, v123
	v_cvt_pk_bf16_f32 v104, v116, v117
; #define PG8_WAIT_V(n) asm volatile("s_waitcnt vmcnt(" #n ")" ::: "memory")
; #define PG8_BAR __builtin_amdgcn_s_barrier()
; template <class Epi>
; __device__ __forceinline__ void gemm_phase(LAS unsigned char* lds, const Gemm g, const StaticOrder& S, const Epi& E) {
;     ...
;         E(acc, cur, wr, wc, fr, fq);
;         if (!has_next) break;
; #pragma unroll
;         for (int a = 0; a < 2; ++a)
; #pragma unroll
;             for (int b = 0; b < 2; ++b)
; #pragma unroll
;                 for (int m = 0; m < 4; ++m)
; #pragma unroll
;                     for (int n = 0; n < 2; ++n) acc[a][b][m][n] = (f32x4){0.f, 0.f, 0.f, 0.f};
;         cur = nxt; cA = nA; cB = nB; ++ui;
;     }
;     PG8_WAIT_V(0);
;     if (wr == 0) PG8_BAR;
;     PG8_BAR;
; __device__ __forceinline__ void phase_final(const Params& p) {
;     const int tid = threadIdx.x, lane = tid & 63, wid = tid >> 6;
;     f32x4 fg0[4], fg1[4];
; #pragma unroll
;     for (int i = 0; i < 4; ++i) { const int c = i * 512 + lane * 8; fg0[i] = *(const f32x4*)(p.final_g + c); fg1[i] = *(const f32x4*)(p.final_g + c + 4); }
	v_cvt_pk_bf16_f32 v105, v118, v119
	v_cvt_pk_bf16_f32 v106, v112, v113
	v_cvt_pk_bf16_f32 v107, v114, v115
	v_cvt_pk_bf16_f32 v88, v100, v101
	v_cvt_pk_bf16_f32 v89, v102, v103
	v_cvt_pk_bf16_f32 v90, v96, v97
	v_cvt_pk_bf16_f32 v91, v98, v99
	global_store_dwordx4 v[92:93], v[76:79], off offset:256
	v_cvt_pk_bf16_f32 v74, v80, v81
	v_cvt_pk_bf16_f32 v75, v82, v83
	v_lshl_add_u64 v[76:77], v[72:73], 0, v[158:159]
	v_cvt_pk_bf16_f32 v72, v84, v85
	v_cvt_pk_bf16_f32 v73, v86, v87
	v_cvt_pk_bf16_f32 v71, v66, v67
	v_cvt_pk_bf16_f32 v63, v58, v59
	v_cvt_pk_bf16_f32 v40, v52, v53
	v_cvt_pk_bf16_f32 v41, v54, v55
	v_cvt_pk_bf16_f32 v42, v48, v49
	v_cvt_pk_bf16_f32 v43, v50, v51
	v_cvt_pk_bf16_f32 v24, v36, v37
	v_cvt_pk_bf16_f32 v25, v38, v39
	v_cvt_pk_bf16_f32 v26, v32, v33
	v_cvt_pk_bf16_f32 v27, v34, v35
	v_lshl_add_u64 v[12:13], v[160:161], 0, s[18:19]
	v_cvt_pk_bf16_f32 v8, v20, v21
	v_cvt_pk_bf16_f32 v9, v22, v23
	v_cvt_pk_bf16_f32 v10, v16, v17
	v_cvt_pk_bf16_f32 v11, v18, v19
	v_cvt_pk_bf16_f32 v4, v4, v5
	v_cvt_pk_bf16_f32 v5, v6, v7
	v_cvt_pk_bf16_f32 v6, v0, v1
	v_cvt_pk_bf16_f32 v7, v2, v3
	s_and_b64 vcc, exec, s[8:9]
	s_mov_b32 s60, s22
	s_mov_b32 s20, s24
	s_mov_b64 s[34:35], s[28:29]
	s_mov_b64 s[30:31], s[26:27]
	s_mov_b32 s40, s70
	global_store_dwordx4 v[160:161], v[124:127], off
	global_store_dwordx4 v[108:109], v[104:107], off
	global_store_dwordx4 v[92:93], v[88:91], off
	global_store_dwordx4 v[76:77], v[72:75], off
	global_store_dwordx4 v[76:77], v[68:71], off offset:256
	global_store_dwordx4 v[56:57], v[60:63], off
	global_store_dwordx4 v[46:47], v[40:43], off
	global_store_dwordx4 v[30:31], v[24:27], off
	global_store_dwordx4 v[14:15], v[8:11], off
	global_store_dwordx4 v[12:13], v[4:7], off offset:256
	s_cbranch_vccnz .Lg2_exit
	s_cmp_lg_u32 s49, 4
	s_cbranch_scc1 .LBB0_556
	s_waitcnt vmcnt(0)
	s_barrier
	s_lshr_b32 s8, s42, 6
	s_cmp_lg_u32 s8, 4
	s_cbranch_scc1 .LBB0_556
	buffer_wbl2 sc1
	s_waitcnt vmcnt(0)
	s_mov_b64 s[8:9], exec
	s_mov_b64 exec, 1
	v_mov_b32_e32 v0, 0
	v_mov_b32_e32 v1, 1
	global_atomic_add v0, v1, s[36:37] offset:256
	s_mov_b64 exec, s[8:9]
	s_branch .LBB0_556
.Lg2_exit:
	s_waitcnt vmcnt(0)
	s_cmpk_gt_u32 s42, 0xff
	s_cbranch_scc1 .LBB0_563
	s_barrier
.LBB0_563:
	s_barrier
	s_cmp_lt_u32 s40, 64
	s_cbranch_scc1 .LBB0_564
	s_cmp_gt_u32 s42, 63
	s_cbranch_scc1 .Lfin1_sync
	buffer_wbl2 sc1
	s_waitcnt vmcnt(0)
	s_mov_b64 s[2:3], exec
	s_mov_b64 exec, 1
	v_mov_b32_e32 v0, 0
	v_mov_b32_e32 v1, 1
	global_atomic_add v0, v1, s[36:37] offset:256
	s_mov_b32 s4, 0
.Lfin1_poll:
	global_load_dword v2, v0, s[36:37] offset:256 sc1
	s_waitcnt vmcnt(0)
	v_readfirstlane_b32 s5, v2
	s_nop 3
	s_cmp_ge_u32 s5, 0x100
	s_cbranch_scc1 .Lfin1_polled
	s_sleep 2
	s_add_i32 s4, s4, 1
	s_cmp_lt_u32 s4, 0x800
	s_cbranch_scc1 .Lfin1_poll
.Lfin1_polled:
	s_mov_b64 exec, s[2:3]
	buffer_inv sc1
	s_waitcnt vmcnt(0)
.Lfin1_sync:
	s_barrier
	s_load_dwordx4 s[4:7], s[0:1], 0xa8
	s_load_dwordx4 s[8:11], s[0:1], 0x0
	v_and_b32_e32 v36, 0x1f8, v131
	v_lshlrev_b32_e32 v16, 2, v36
	v_or_b32_e32 v38, 0x400, v36
	s_waitcnt lgkmcnt(0)
	global_load_dwordx4 v[0:3], v16, s[4:5] offset:16
	global_load_dwordx4 v[4:7], v16, s[4:5]
	global_load_dwordx4 v[8:11], v16, s[4:5] offset:2064
	global_load_dwordx4 v[12:15], v16, s[4:5] offset:2048
	v_or_b32_e32 v46, 0x600, v36
	v_lshlrev_b32_e32 v24, 2, v38
	v_lshlrev_b32_e32 v32, 2, v46
	global_load_dwordx4 v[16:19], v24, s[4:5] offset:16
	global_load_dwordx4 v[20:23], v24, s[4:5]
	s_nop 0
	global_load_dwordx4 v[24:27], v32, s[4:5] offset:16
	global_load_dwordx4 v[28:31], v32, s[4:5]
	v_mbcnt_hi_u32_b32 v32, -1, v129
	v_and_b32_e32 v34, 64, v32
	v_add_u32_e32 v34, 64, v34
	v_xor_b32_e32 v35, 32, v32
	v_cmp_lt_i32_e32 vcc, v35, v34
	s_load_dwordx2 s[48:49], s[0:1], 0xe8
	v_mov_b32_e32 v33, 0
	v_cndmask_b32_e32 v35, v32, v35, vcc
	v_lshlrev_b32_e32 v40, 2, v35
	v_xor_b32_e32 v35, 16, v32
	v_cmp_lt_i32_e32 vcc, v35, v34
	s_mov_b32 s3, 0x8000
	v_cndmask_b32_e32 v35, v32, v35, vcc
	v_lshlrev_b32_e32 v41, 2, v35
	v_xor_b32_e32 v35, 8, v32
	v_cmp_lt_i32_e32 vcc, v35, v34
	s_mov_b32 s4, 0x800000
	s_mov_b32 s5, 0x87ff
	v_cndmask_b32_e32 v35, v32, v35, vcc
	v_lshlrev_b32_e32 v42, 2, v35
	v_xor_b32_e32 v35, 4, v32
	v_cmp_lt_i32_e32 vcc, v35, v34
	s_nop 1
	v_cndmask_b32_e32 v35, v32, v35, vcc
	v_lshlrev_b32_e32 v43, 2, v35
	v_xor_b32_e32 v35, 2, v32
	v_cmp_lt_i32_e32 vcc, v35, v34
	s_nop 1
	v_cndmask_b32_e32 v35, v32, v35, vcc
	v_lshlrev_b32_e32 v44, 2, v35
	v_xor_b32_e32 v35, 1, v32
	v_cmp_lt_i32_e32 vcc, v35, v34
	s_nop 1
	v_cndmask_b32_e32 v32, v32, v35, vcc
	v_lshlrev_b32_e32 v45, 2, v32
	v_lshlrev_b32_e32 v32, 1, v36
	s_waitcnt lgkmcnt(0)
	v_lshl_add_u64 v[34:35], s[48:49], 0, v[32:33]
	v_lshlrev_b32_e32 v32, 2, v36
	v_lshlrev_b32_e32 v36, 2, v38
	v_lshlrev_b32_e32 v38, 2, v46
	v_mov_b32_e32 v46, 0x358637bd
	s_lshr_b32 s44, s42, 6
	s_lshl_b32 s45, s40, 3
	s_add_i32 s45, s45, s44
	s_add_i32 s45, s45, 0xfffffe00
; __device__ __forceinline__ float bf_lo(unsigned u) { return __uint_as_float(u << 16); }
; __device__ __forceinline__ float bf_hi(unsigned u) { return __uint_as_float(u & 0xffff0000u); }
; __device__ __forceinline__ void phase_final(const Params& p) {
;     ...
;     for (int row = blockIdx.x * 8 + wid; row < MT; row += gridDim.x * 8) {
;         const bf16_t* yr = p.QG + (size_t)row * DM; float* xr = p.out + (size_t)row * DM; const float* xi = xrow(p, row);
;         u32x4 v[4]; f32x4 y0[4], y1[4]; float ss = 0.f;
; #pragma unroll
;         for (int i = 0; i < 4; ++i) { const int c = i * 512 + lane * 8; v[i] = *(const u32x4*)(yr + c); y0[i] = *(const f32x4*)(xi + c); y1[i] = *(const f32x4*)(xi + c + 4); }
; #pragma unroll
;         for (int i = 0; i < 4; ++i) {
;             y0[i] += (f32x4){bf_lo(v[i].x), bf_hi(v[i].x), bf_lo(v[i].y), bf_hi(v[i].y)}; y1[i] += (f32x4){bf_lo(v[i].z), bf_hi(v[i].z), bf_lo(v[i].w), bf_hi(v[i].w)};
;             ss += y0[i][0] * y0[i][0] + y0[i][1] * y0[i][1] + y0[i][2] * y0[i][2] + y0[i][3] * y0[i][3] + y1[i][0] * y1[i][0] + y1[i][1] * y1[i][1] + y1[i][2] * y1[i][2] + y1[i][3] * y1[i][3]; }
.Lfin1_loop:
	s_lshr_b32 s46, s45, 11
	s_max_u32 s46, s46, 1
	s_add_i32 s46, s46, -1
	s_lshl_b32 s46, s46, 11
	s_add_i32 s46, s46, s45
	v_mov_b32_e32 v110, s46
	v_ashrrev_i32_e32 v111, 31, v110
	v_add_u32_e32 v37, 0xffff8000, v110
	v_cmp_gt_i32_e32 vcc, s3, v110
	v_lshlrev_b64 v[48:49], 12, v[110:111]
	v_mov_b32_e32 v39, s11
	v_mov_b32_e32 v47, s9
	v_mov_b32_e32 v64, s10
	v_mov_b32_e32 v66, s8
	v_cndmask_b32_e32 v63, 0, v111, vcc
	v_cndmask_b32_e32 v62, v37, v110, vcc
	v_lshl_add_u64 v[60:61], v[34:35], 0, v[48:49]
	v_cndmask_b32_e32 v65, v39, v47, vcc
	v_cndmask_b32_e32 v64, v64, v66, vcc
	v_lshlrev_b64 v[66:67], 13, v[62:63]
	global_load_dwordx4 v[48:51], v[60:61], off
	global_load_dwordx4 v[52:55], v[60:61], off offset:1024
	v_lshl_add_u64 v[88:89], v[64:65], 0, v[66:67]
	v_lshl_add_u64 v[80:81], v[88:89], 0, v[32:33]
	global_load_dwordx4 v[56:59], v[60:61], off offset:2048
	v_mov_b32_e32 v37, v33
	global_load_dwordx4 v[60:63], v[60:61], off offset:3072
	s_nop 0
	global_load_dwordx4 v[64:67], v[80:81], off
	global_load_dwordx4 v[68:71], v[80:81], off offset:16
	global_load_dwordx4 v[72:75], v[80:81], off offset:2048
	global_load_dwordx4 v[76:79], v[80:81], off offset:2064
	v_lshl_add_u64 v[90:91], v[88:89], 0, v[36:37]
	global_load_dwordx4 v[80:83], v[90:91], off
	global_load_dwordx4 v[84:87], v[90:91], off offset:16
	v_mov_b32_e32 v39, v33
	v_lshl_add_u64 v[96:97], v[88:89], 0, v[38:39]
	global_load_dwordx4 v[88:91], v[96:97], off
	global_load_dwordx4 v[92:95], v[96:97], off offset:16
	s_waitcnt vmcnt(11)
	v_lshlrev_b32_e32 v96, 16, v48
	v_and_b32_e32 v97, 0xffff0000, v48
	v_lshlrev_b32_e32 v48, 16, v49
	v_and_b32_e32 v49, 0xffff0000, v49
	v_lshlrev_b32_e32 v98, 16, v50
	v_and_b32_e32 v99, 0xffff0000, v50
	v_lshlrev_b32_e32 v50, 16, v51
	v_and_b32_e32 v51, 0xffff0000, v51
	s_waitcnt vmcnt(10)
	v_lshlrev_b32_e32 v100, 16, v52
	v_and_b32_e32 v101, 0xffff0000, v52
	v_lshlrev_b32_e32 v102, 16, v54
	v_and_b32_e32 v103, 0xffff0000, v54
	v_lshlrev_b32_e32 v54, 16, v55
	v_and_b32_e32 v55, 0xffff0000, v55
	s_waitcnt vmcnt(7)
	v_pk_add_f32 v[48:49], v[66:67], v[48:49]
	v_pk_add_f32 v[64:65], v[64:65], v[96:97]
	s_waitcnt vmcnt(6)
	v_pk_add_f32 v[66:67], v[70:71], v[50:51]
	s_waitcnt vmcnt(5)
	v_pk_add_f32 v[70:71], v[72:73], v[100:101]
	v_lshlrev_b32_e32 v52, 16, v53
	v_and_b32_e32 v53, 0xffff0000, v53
	s_waitcnt vmcnt(4)
	v_pk_add_f32 v[54:55], v[78:79], v[54:55]
	v_mov_b32_e32 v78, v65
	v_mov_b32_e32 v79, v71
	v_lshlrev_b32_e32 v104, 16, v56
	v_and_b32_e32 v105, 0xffff0000, v56
	v_pk_add_f32 v[52:53], v[74:75], v[52:53]
	v_mov_b32_e32 v50, v64
	v_mov_b32_e32 v51, v70
	v_pk_mul_f32 v[78:79], v[78:79], v[78:79]
	v_lshlrev_b32_e32 v56, 16, v57
	v_and_b32_e32 v57, 0xffff0000, v57
	s_waitcnt vmcnt(3)
	v_pk_add_f32 v[74:75], v[80:81], v[104:105]
	v_mov_b32_e32 v80, v48
	v_mov_b32_e32 v81, v52
	v_pk_fma_f32 v[50:51], v[50:51], v[50:51], v[78:79]
	v_lshlrev_b32_e32 v106, 16, v58
	v_and_b32_e32 v107, 0xffff0000, v58
	v_lshlrev_b32_e32 v108, 16, v60
	v_and_b32_e32 v109, 0xffff0000, v60
	v_pk_add_f32 v[68:69], v[68:69], v[98:99]
	v_pk_add_f32 v[72:73], v[76:77], v[102:103]
	v_pk_add_f32 v[56:57], v[82:83], v[56:57]
	v_mov_b32_e32 v82, v49
	v_mov_b32_e32 v83, v53
	v_pk_fma_f32 v[50:51], v[80:81], v[80:81], v[50:51]
	s_waitcnt vmcnt(2)
	v_pk_add_f32 v[76:77], v[84:85], v[106:107]
	v_mov_b32_e32 v84, v68
	v_mov_b32_e32 v85, v72
	v_pk_fma_f32 v[50:51], v[82:83], v[82:83], v[50:51]
	s_waitcnt vmcnt(1)
	v_pk_add_f32 v[78:79], v[88:89], v[108:109]
	v_lshlrev_b32_e32 v60, 16, v61
	v_pk_fma_f32 v[50:51], v[84:85], v[84:85], v[50:51]
	v_and_b32_e32 v61, 0xffff0000, v61
	v_mov_b32_e32 v84, v75
	v_mov_b32_e32 v85, v79
	v_pk_add_f32 v[60:61], v[90:91], v[60:61]
	v_mov_b32_e32 v82, v74
	v_mov_b32_e32 v83, v78
	v_pk_mul_f32 v[84:85], v[84:85], v[84:85]
	v_lshlrev_b32_e32 v80, 16, v62
	v_and_b32_e32 v81, 0xffff0000, v62
	v_pk_fma_f32 v[82:83], v[82:83], v[82:83], v[84:85]
	v_mov_b32_e32 v84, v56
	v_mov_b32_e32 v85, v60
	v_lshlrev_b32_e32 v58, 16, v59
	v_and_b32_e32 v59, 0xffff0000, v59
	s_waitcnt vmcnt(0)
; __device__ __forceinline__ void phase_final(const Params& p) {
;     ...
;             ss += y0[i][0] * y0[i][0] + y0[i][1] * y0[i][1] + y0[i][2] * y0[i][2] + y0[i][3] * y0[i][3] + y1[i][0] * y1[i][0] + y1[i][1] * y1[i][1] + y1[i][2] * y1[i][2] + y1[i][3] * y1[i][3]; }
;         ss = wave_sum(ss);
;         const float rs = rsqrtf(ss * (1.0f / DM) + 1e-6f);
; #pragma unroll
;         for (int i = 0; i < 4; ++i) { const int c = i * 512 + lane * 8;
;             *(f32x4*)(xr + c) = y0[i] * rs * fg0[i]; *(f32x4*)(xr + c + 4) = y1[i] * rs * fg1[i]; }
;     }
	v_pk_add_f32 v[80:81], v[92:93], v[80:81]
	v_pk_fma_f32 v[82:83], v[84:85], v[84:85], v[82:83]
	v_mov_b32_e32 v84, v57
	v_mov_b32_e32 v85, v61
	v_pk_add_f32 v[58:59], v[86:87], v[58:59]
	v_mov_b32_e32 v86, v69
	v_mov_b32_e32 v87, v73
	v_lshlrev_b32_e32 v62, 16, v63
	v_and_b32_e32 v63, 0xffff0000, v63
	v_pk_fma_f32 v[82:83], v[84:85], v[84:85], v[82:83]
	v_mov_b32_e32 v84, v76
	v_mov_b32_e32 v85, v80
	v_mov_b32_e32 v96, v66
	v_mov_b32_e32 v97, v54
	v_pk_fma_f32 v[50:51], v[86:87], v[86:87], v[50:51]
	v_pk_add_f32 v[62:63], v[94:95], v[62:63]
	v_pk_fma_f32 v[82:83], v[84:85], v[84:85], v[82:83]
	v_mov_b32_e32 v84, v77
	v_mov_b32_e32 v85, v81
	v_mov_b32_e32 v98, v67
	v_mov_b32_e32 v99, v55
	v_pk_fma_f32 v[50:51], v[96:97], v[96:97], v[50:51]
	v_pk_fma_f32 v[82:83], v[84:85], v[84:85], v[82:83]
	v_mov_b32_e32 v84, v58
	v_mov_b32_e32 v85, v62
	v_pk_fma_f32 v[50:51], v[98:99], v[98:99], v[50:51]
	v_pk_fma_f32 v[82:83], v[84:85], v[84:85], v[82:83]
	v_mov_b32_e32 v84, v59
	v_mov_b32_e32 v85, v63
	v_pk_fma_f32 v[82:83], v[84:85], v[84:85], v[82:83]
	v_add_f32_e32 v47, v50, v51
	v_add_f32_e32 v47, v47, v82
	v_add_f32_e32 v47, v47, v83
	ds_bpermute_b32 v50, v40, v47
	s_waitcnt lgkmcnt(0)
	v_add_f32_e32 v47, v47, v50
	ds_bpermute_b32 v50, v41, v47
	s_waitcnt lgkmcnt(0)
	v_add_f32_e32 v47, v47, v50
	ds_bpermute_b32 v50, v42, v47
	s_waitcnt lgkmcnt(0)
	v_add_f32_e32 v47, v47, v50
	ds_bpermute_b32 v50, v43, v47
	s_waitcnt lgkmcnt(0)
	v_add_f32_e32 v47, v47, v50
	ds_bpermute_b32 v50, v44, v47
	s_waitcnt lgkmcnt(0)
	v_add_f32_e32 v47, v47, v50
	ds_bpermute_b32 v50, v45, v47
	s_waitcnt lgkmcnt(0)
	v_add_f32_e32 v47, v47, v50
	v_fmamk_f32 v47, v47, 0x3a000000, v46
	v_mul_f32_e32 v50, 0x4b800000, v47
	v_cmp_gt_f32_e32 vcc, s4, v47
	s_nop 1
	v_cndmask_b32_e32 v47, v47, v50, vcc
	v_rsq_f32_e32 v47, v47
	v_lshlrev_b64 v[50:51], 13, v[110:111]
	v_lshl_add_u64 v[82:83], s[6:7], 0, v[50:51]
	v_mul_f32_e32 v50, 0x45800000, v47
	v_cndmask_b32_e32 v84, v47, v50, vcc
	v_pk_mul_f32 v[64:65], v[64:65], v[84:85] op_sel_hi:[1,0]
	v_pk_mul_f32 v[48:49], v[48:49], v[84:85] op_sel_hi:[1,0]
	v_pk_mul_f32 v[50:51], v[6:7], v[48:49]
	v_pk_mul_f32 v[48:49], v[4:5], v[64:65]
	v_lshl_add_u64 v[64:65], v[82:83], 0, v[32:33]
	global_store_dwordx4 v[64:65], v[48:51], off
	s_nop 0
	s_nop 0
	v_pk_mul_f32 v[48:49], v[68:69], v[84:85] op_sel_hi:[1,0]
	v_pk_mul_f32 v[50:51], v[66:67], v[84:85] op_sel_hi:[1,0]
	v_pk_mul_f32 v[48:49], v[0:1], v[48:49]
	v_pk_mul_f32 v[50:51], v[2:3], v[50:51]
	global_store_dwordx4 v[64:65], v[48:51], off offset:16
	s_nop 1
	v_pk_mul_f32 v[48:49], v[70:71], v[84:85] op_sel_hi:[1,0]
	v_pk_mul_f32 v[50:51], v[52:53], v[84:85] op_sel_hi:[1,0]
	v_pk_mul_f32 v[48:49], v[12:13], v[48:49]
	v_pk_mul_f32 v[50:51], v[14:15], v[50:51]
	global_store_dwordx4 v[64:65], v[48:51], off offset:2048
	v_lshl_add_u64 v[52:53], v[82:83], 0, v[36:37]
	s_nop 0
	v_pk_mul_f32 v[48:49], v[72:73], v[84:85] op_sel_hi:[1,0]
	v_pk_mul_f32 v[50:51], v[54:55], v[84:85] op_sel_hi:[1,0]
	v_pk_mul_f32 v[48:49], v[8:9], v[48:49]
	v_pk_mul_f32 v[50:51], v[10:11], v[50:51]
	global_store_dwordx4 v[64:65], v[48:51], off offset:2064
	s_nop 1
	v_pk_mul_f32 v[48:49], v[74:75], v[84:85] op_sel_hi:[1,0]
	v_pk_mul_f32 v[50:51], v[56:57], v[84:85] op_sel_hi:[1,0]
	v_pk_mul_f32 v[48:49], v[20:21], v[48:49]
	v_pk_mul_f32 v[50:51], v[22:23], v[50:51]
	global_store_dwordx4 v[52:53], v[48:51], off
	s_nop 1
	v_pk_mul_f32 v[48:49], v[76:77], v[84:85] op_sel_hi:[1,0]
	v_pk_mul_f32 v[50:51], v[58:59], v[84:85] op_sel_hi:[1,0]
	v_pk_mul_f32 v[48:49], v[16:17], v[48:49]
	v_pk_mul_f32 v[50:51], v[18:19], v[50:51]
	global_store_dwordx4 v[52:53], v[48:51], off offset:16
	v_lshl_add_u64 v[52:53], v[82:83], 0, v[38:39]
	s_nop 0
	v_pk_mul_f32 v[48:49], v[78:79], v[84:85] op_sel_hi:[1,0]
	v_pk_mul_f32 v[50:51], v[60:61], v[84:85] op_sel_hi:[1,0]
	v_pk_mul_f32 v[48:49], v[28:29], v[48:49]
	v_pk_mul_f32 v[50:51], v[30:31], v[50:51]
	global_store_dwordx4 v[52:53], v[48:51], off
	s_nop 1
	v_pk_mul_f32 v[48:49], v[80:81], v[84:85] op_sel_hi:[1,0]
	v_pk_mul_f32 v[50:51], v[62:63], v[84:85] op_sel_hi:[1,0]
	v_pk_mul_f32 v[48:49], v[24:25], v[48:49]
	v_pk_mul_f32 v[50:51], v[26:27], v[50:51]
	global_store_dwordx4 v[52:53], v[48:51], off offset:16
	s_addk_i32 s45, 0x600
	s_cmpk_lt_u32 s45, 0x3000
	s_cbranch_scc1 .Lfin1_loop

; __device__ __forceinline__ float bf_lo(unsigned u) { return __uint_as_float(u << 16); }
; __device__ __forceinline__ float bf_hi(unsigned u) { return __uint_as_float(u & 0xffff0000u); }
; __device__ __forceinline__ void phase_final(const Params& p) {
;     const int tid = threadIdx.x, lane = tid & 63, wid = tid >> 6;
;     f32x4 fg0[4], fg1[4];
; #pragma unroll
;     for (int i = 0; i < 4; ++i) { const int c = i * 512 + lane * 8; fg0[i] = *(const f32x4*)(p.final_g + c); fg1[i] = *(const f32x4*)(p.final_g + c + 4); }
;     for (int row = blockIdx.x * 8 + wid; row < MT; row += gridDim.x * 8) {
;         const bf16_t* yr = p.QG + (size_t)row * DM; float* xr = p.out + (size_t)row * DM; const float* xi = xrow(p, row);
;         u32x4 v[4]; f32x4 y0[4], y1[4]; float ss = 0.f;
; #pragma unroll
;         for (int i = 0; i < 4; ++i) { const int c = i * 512 + lane * 8; v[i] = *(const u32x4*)(yr + c); y0[i] = *(const f32x4*)(xi + c); y1[i] = *(const f32x4*)(xi + c + 4); }
; #pragma unroll
;         for (int i = 0; i < 4; ++i) {
;             y0[i] += (f32x4){bf_lo(v[i].x), bf_hi(v[i].x), bf_lo(v[i].y), bf_hi(v[i].y)}; y1[i] += (f32x4){bf_lo(v[i].z), bf_hi(v[i].z), bf_lo(v[i].w), bf_hi(v[i].w)};
;             ss += y0[i][0] * y0[i][0] + y0[i][1] * y0[i][1] + y0[i][2] * y0[i][2] + y0[i][3] * y0[i][3] + y1[i][0] * y1[i][0] + y1[i][1] * y1[i][1] + y1[i][2] * y1[i][2] + y1[i][3] * y1[i][3]; }
.LBB0_616:
	s_or_b64 exec, exec, s[2:3]
	v_readlane_b32 s4, v244, 4
	v_readlane_b32 s5, v244, 5
	s_barrier
	s_and_saveexec_b64 s[2:3], s[4:5]
	s_cbranch_execz .LBB0_619
	s_load_dwordx4 s[4:7], s[0:1], 0xa8
	s_load_dwordx4 s[8:11], s[0:1], 0x0
	v_and_b32_e32 v36, 0x1f8, v131
	v_lshlrev_b32_e32 v16, 2, v36
	v_or_b32_e32 v38, 0x400, v36
	s_waitcnt lgkmcnt(0)
	global_load_dwordx4 v[0:3], v16, s[4:5] offset:16
	global_load_dwordx4 v[4:7], v16, s[4:5]
	global_load_dwordx4 v[8:11], v16, s[4:5] offset:2064
	global_load_dwordx4 v[12:15], v16, s[4:5] offset:2048
	v_or_b32_e32 v46, 0x600, v36
	v_lshlrev_b32_e32 v24, 2, v38
	v_lshlrev_b32_e32 v32, 2, v46
	global_load_dwordx4 v[16:19], v24, s[4:5] offset:16
	global_load_dwordx4 v[20:23], v24, s[4:5]
	s_nop 0
	global_load_dwordx4 v[24:27], v32, s[4:5] offset:16
	global_load_dwordx4 v[28:31], v32, s[4:5]
	v_mbcnt_hi_u32_b32 v32, -1, v129
	v_and_b32_e32 v34, 64, v32
	v_add_u32_e32 v34, 64, v34
	v_xor_b32_e32 v35, 32, v32
	v_cmp_lt_i32_e32 vcc, v35, v34
	s_load_dwordx2 s[0:1], s[0:1], 0xe8
	v_mov_b32_e32 v33, 0
	v_cndmask_b32_e32 v35, v32, v35, vcc
	v_lshlrev_b32_e32 v40, 2, v35
	v_xor_b32_e32 v35, 16, v32
	v_cmp_lt_i32_e32 vcc, v35, v34
	s_lshl_b32 s2, s38, 3
	s_mov_b32 s3, 0x8000
	v_cndmask_b32_e32 v35, v32, v35, vcc
	v_lshlrev_b32_e32 v41, 2, v35
	v_xor_b32_e32 v35, 8, v32
	v_cmp_lt_i32_e32 vcc, v35, v34
	s_mov_b32 s4, 0x800000
	s_mov_b32 s5, 0x87ff
	v_cndmask_b32_e32 v35, v32, v35, vcc
	v_lshlrev_b32_e32 v42, 2, v35
	v_xor_b32_e32 v35, 4, v32
	v_cmp_lt_i32_e32 vcc, v35, v34
	s_nop 1
	v_cndmask_b32_e32 v35, v32, v35, vcc
	v_lshlrev_b32_e32 v43, 2, v35
	v_xor_b32_e32 v35, 2, v32
	v_cmp_lt_i32_e32 vcc, v35, v34
	s_nop 1
	v_cndmask_b32_e32 v35, v32, v35, vcc
	v_lshlrev_b32_e32 v44, 2, v35
	v_xor_b32_e32 v35, 1, v32
	v_cmp_lt_i32_e32 vcc, v35, v34
	s_nop 1
	v_cndmask_b32_e32 v32, v32, v35, vcc
	v_lshlrev_b32_e32 v45, 2, v32
	v_lshlrev_b32_e32 v32, 1, v36
	s_waitcnt lgkmcnt(0)
	v_lshl_add_u64 v[34:35], s[0:1], 0, v[32:33]
	s_mov_b64 s[0:1], 0
	v_lshlrev_b32_e32 v32, 2, v36
	v_lshlrev_b32_e32 v36, 2, v38
	v_lshlrev_b32_e32 v38, 2, v46
	v_mov_b32_e32 v46, 0x358637bd
	v_add_u32_e32 v128, 0x1000, v128
	s_nop 0
	v_readfirstlane_b32 s13, v128
	s_nop 3
.LBB0_618:
	v_ashrrev_i32_e32 v129, 31, v128
	v_add_u32_e32 v37, 0xffff8000, v128
	v_cmp_gt_i32_e32 vcc, s3, v128
	v_lshlrev_b64 v[48:49], 12, v[128:129]
	v_mov_b32_e32 v39, s11
	v_mov_b32_e32 v47, s9
	v_mov_b32_e32 v64, s10
	v_mov_b32_e32 v66, s8
	v_cndmask_b32_e32 v63, 0, v129, vcc
	v_cndmask_b32_e32 v62, v37, v128, vcc
	v_lshl_add_u64 v[60:61], v[34:35], 0, v[48:49]
	v_cndmask_b32_e32 v65, v39, v47, vcc
	v_cndmask_b32_e32 v64, v64, v66, vcc
	v_lshlrev_b64 v[66:67], 13, v[62:63]
	global_load_dwordx4 v[48:51], v[60:61], off
	global_load_dwordx4 v[52:55], v[60:61], off offset:1024
	v_lshl_add_u64 v[88:89], v[64:65], 0, v[66:67]
	v_lshl_add_u64 v[80:81], v[88:89], 0, v[32:33]
	global_load_dwordx4 v[56:59], v[60:61], off offset:2048
	v_mov_b32_e32 v37, v33
	global_load_dwordx4 v[60:63], v[60:61], off offset:3072
	s_nop 0
	global_load_dwordx4 v[64:67], v[80:81], off
	global_load_dwordx4 v[68:71], v[80:81], off offset:16
	global_load_dwordx4 v[72:75], v[80:81], off offset:2048
	global_load_dwordx4 v[76:79], v[80:81], off offset:2064
	v_lshl_add_u64 v[90:91], v[88:89], 0, v[36:37]
	global_load_dwordx4 v[80:83], v[90:91], off
	global_load_dwordx4 v[84:87], v[90:91], off offset:16
	v_mov_b32_e32 v39, v33
	v_lshl_add_u64 v[96:97], v[88:89], 0, v[38:39]
	global_load_dwordx4 v[88:91], v[96:97], off
	global_load_dwordx4 v[92:95], v[96:97], off offset:16
	s_waitcnt vmcnt(11)
	v_lshlrev_b32_e32 v96, 16, v48
	v_and_b32_e32 v97, 0xffff0000, v48
	v_lshlrev_b32_e32 v48, 16, v49
	v_and_b32_e32 v49, 0xffff0000, v49
	v_lshlrev_b32_e32 v98, 16, v50
	v_and_b32_e32 v99, 0xffff0000, v50
	v_lshlrev_b32_e32 v50, 16, v51
	v_and_b32_e32 v51, 0xffff0000, v51
	s_waitcnt vmcnt(10)
	v_lshlrev_b32_e32 v100, 16, v52
	v_and_b32_e32 v101, 0xffff0000, v52
	v_lshlrev_b32_e32 v102, 16, v54
	v_and_b32_e32 v103, 0xffff0000, v54
	v_lshlrev_b32_e32 v54, 16, v55
	v_and_b32_e32 v55, 0xffff0000, v55
	s_waitcnt vmcnt(7)
	v_pk_add_f32 v[48:49], v[66:67], v[48:49]
	v_pk_add_f32 v[64:65], v[64:65], v[96:97]
	s_waitcnt vmcnt(6)
	v_pk_add_f32 v[66:67], v[70:71], v[50:51]
	s_waitcnt vmcnt(5)
	v_pk_add_f32 v[70:71], v[72:73], v[100:101]
	v_lshlrev_b32_e32 v52, 16, v53
	v_and_b32_e32 v53, 0xffff0000, v53
	s_waitcnt vmcnt(4)
	v_pk_add_f32 v[54:55], v[78:79], v[54:55]
	v_mov_b32_e32 v78, v65
	v_mov_b32_e32 v79, v71
	v_lshlrev_b32_e32 v104, 16, v56
	v_and_b32_e32 v105, 0xffff0000, v56
	v_pk_add_f32 v[52:53], v[74:75], v[52:53]
	v_mov_b32_e32 v50, v64
	v_mov_b32_e32 v51, v70
	v_pk_mul_f32 v[78:79], v[78:79], v[78:79]
	v_lshlrev_b32_e32 v56, 16, v57
	v_and_b32_e32 v57, 0xffff0000, v57
	s_waitcnt vmcnt(3)
	v_pk_add_f32 v[74:75], v[80:81], v[104:105]
	v_mov_b32_e32 v80, v48
	v_mov_b32_e32 v81, v52
	v_pk_fma_f32 v[50:51], v[50:51], v[50:51], v[78:79]
	v_lshlrev_b32_e32 v106, 16, v58
	v_and_b32_e32 v107, 0xffff0000, v58
	v_lshlrev_b32_e32 v108, 16, v60
	v_and_b32_e32 v109, 0xffff0000, v60
	v_pk_add_f32 v[68:69], v[68:69], v[98:99]
	v_pk_add_f32 v[72:73], v[76:77], v[102:103]
	v_pk_add_f32 v[56:57], v[82:83], v[56:57]
	v_mov_b32_e32 v82, v49
	v_mov_b32_e32 v83, v53
	v_pk_fma_f32 v[50:51], v[80:81], v[80:81], v[50:51]
	s_waitcnt vmcnt(2)
; __device__ __forceinline__ void phase_final(const Params& p) {
;     ...
;             ss += y0[i][0] * y0[i][0] + y0[i][1] * y0[i][1] + y0[i][2] * y0[i][2] + y0[i][3] * y0[i][3] + y1[i][0] * y1[i][0] + y1[i][1] * y1[i][1] + y1[i][2] * y1[i][2] + y1[i][3] * y1[i][3]; }
;         ss = wave_sum(ss);
;         const float rs = rsqrtf(ss * (1.0f / DM) + 1e-6f);
; #pragma unroll
;         for (int i = 0; i < 4; ++i) { const int c = i * 512 + lane * 8;
;             *(f32x4*)(xr + c) = y0[i] * rs * fg0[i]; *(f32x4*)(xr + c + 4) = y1[i] * rs * fg1[i]; }
;     }
	v_pk_add_f32 v[76:77], v[84:85], v[106:107]
	v_mov_b32_e32 v84, v68
	v_mov_b32_e32 v85, v72
	v_pk_fma_f32 v[50:51], v[82:83], v[82:83], v[50:51]
	s_waitcnt vmcnt(1)
	v_pk_add_f32 v[78:79], v[88:89], v[108:109]
	v_lshlrev_b32_e32 v60, 16, v61
	v_pk_fma_f32 v[50:51], v[84:85], v[84:85], v[50:51]
	v_and_b32_e32 v61, 0xffff0000, v61
	v_mov_b32_e32 v84, v75
	v_mov_b32_e32 v85, v79
	v_pk_add_f32 v[60:61], v[90:91], v[60:61]
	v_mov_b32_e32 v82, v74
	v_mov_b32_e32 v83, v78
	v_pk_mul_f32 v[84:85], v[84:85], v[84:85]
	v_lshlrev_b32_e32 v80, 16, v62
	v_and_b32_e32 v81, 0xffff0000, v62
	v_pk_fma_f32 v[82:83], v[82:83], v[82:83], v[84:85]
	v_mov_b32_e32 v84, v56
	v_mov_b32_e32 v85, v60
	v_lshlrev_b32_e32 v58, 16, v59
	v_and_b32_e32 v59, 0xffff0000, v59
	s_waitcnt vmcnt(0)
	v_pk_add_f32 v[80:81], v[92:93], v[80:81]
	v_pk_fma_f32 v[82:83], v[84:85], v[84:85], v[82:83]
	v_mov_b32_e32 v84, v57
	v_mov_b32_e32 v85, v61
	v_pk_add_f32 v[58:59], v[86:87], v[58:59]
	v_mov_b32_e32 v86, v69
	v_mov_b32_e32 v87, v73
	v_lshlrev_b32_e32 v62, 16, v63
	v_and_b32_e32 v63, 0xffff0000, v63
	v_pk_fma_f32 v[82:83], v[84:85], v[84:85], v[82:83]
	v_mov_b32_e32 v84, v76
	v_mov_b32_e32 v85, v80
	v_mov_b32_e32 v96, v66
	v_mov_b32_e32 v97, v54
	v_pk_fma_f32 v[50:51], v[86:87], v[86:87], v[50:51]
	v_pk_add_f32 v[62:63], v[94:95], v[62:63]
	v_pk_fma_f32 v[82:83], v[84:85], v[84:85], v[82:83]
	v_mov_b32_e32 v84, v77
	v_mov_b32_e32 v85, v81
	v_mov_b32_e32 v98, v67
	v_mov_b32_e32 v99, v55
	v_pk_fma_f32 v[50:51], v[96:97], v[96:97], v[50:51]
	v_pk_fma_f32 v[82:83], v[84:85], v[84:85], v[82:83]
	v_mov_b32_e32 v84, v58
	v_mov_b32_e32 v85, v62
	v_pk_fma_f32 v[50:51], v[98:99], v[98:99], v[50:51]
	v_pk_fma_f32 v[82:83], v[84:85], v[84:85], v[82:83]
	v_mov_b32_e32 v84, v59
	v_mov_b32_e32 v85, v63
	v_pk_fma_f32 v[82:83], v[84:85], v[84:85], v[82:83]
	v_add_f32_e32 v47, v50, v51
	v_add_f32_e32 v47, v47, v82
	v_add_f32_e32 v47, v47, v83
	ds_bpermute_b32 v50, v40, v47
	s_waitcnt lgkmcnt(0)
	v_add_f32_e32 v47, v47, v50
	ds_bpermute_b32 v50, v41, v47
	s_waitcnt lgkmcnt(0)
	v_add_f32_e32 v47, v47, v50
	ds_bpermute_b32 v50, v42, v47
	s_waitcnt lgkmcnt(0)
	v_add_f32_e32 v47, v47, v50
	ds_bpermute_b32 v50, v43, v47
	s_waitcnt lgkmcnt(0)
	v_add_f32_e32 v47, v47, v50
	ds_bpermute_b32 v50, v44, v47
	s_waitcnt lgkmcnt(0)
	v_add_f32_e32 v47, v47, v50
	ds_bpermute_b32 v50, v45, v47
	s_waitcnt lgkmcnt(0)
	v_add_f32_e32 v47, v47, v50
	v_fmamk_f32 v47, v47, 0x3a000000, v46
	v_mul_f32_e32 v50, 0x4b800000, v47
	v_cmp_gt_f32_e32 vcc, s4, v47
	s_nop 1
	v_cndmask_b32_e32 v47, v47, v50, vcc
	v_rsq_f32_e32 v47, v47
	v_lshlrev_b64 v[50:51], 13, v[128:129]
	v_lshl_add_u64 v[82:83], s[6:7], 0, v[50:51]
	s_cmpk_lt_u32 s13, 0x5000
	s_cselect_b32 s12, 0x800, 0
	s_addk_i32 s12, 0x800
	s_add_i32 s13, s13, s12
	v_add_u32_e32 v128, s12, v128
	v_mul_f32_e32 v50, 0x45800000, v47
	v_cndmask_b32_e32 v84, v47, v50, vcc
	v_pk_mul_f32 v[64:65], v[64:65], v[84:85] op_sel_hi:[1,0]
	v_pk_mul_f32 v[48:49], v[48:49], v[84:85] op_sel_hi:[1,0]
	v_cmp_lt_i32_e32 vcc, s5, v128
	v_pk_mul_f32 v[50:51], v[6:7], v[48:49]
	v_pk_mul_f32 v[48:49], v[4:5], v[64:65]
	v_lshl_add_u64 v[64:65], v[82:83], 0, v[32:33]
	global_store_dwordx4 v[64:65], v[48:51], off
	s_or_b64 s[0:1], vcc, s[0:1]
	s_nop 0
	v_pk_mul_f32 v[48:49], v[68:69], v[84:85] op_sel_hi:[1,0]
	v_pk_mul_f32 v[50:51], v[66:67], v[84:85] op_sel_hi:[1,0]
	v_pk_mul_f32 v[48:49], v[0:1], v[48:49]
	v_pk_mul_f32 v[50:51], v[2:3], v[50:51]
	global_store_dwordx4 v[64:65], v[48:51], off offset:16
	s_nop 1
	v_pk_mul_f32 v[48:49], v[70:71], v[84:85] op_sel_hi:[1,0]
	v_pk_mul_f32 v[50:51], v[52:53], v[84:85] op_sel_hi:[1,0]
	v_pk_mul_f32 v[48:49], v[12:13], v[48:49]
	v_pk_mul_f32 v[50:51], v[14:15], v[50:51]
	global_store_dwordx4 v[64:65], v[48:51], off offset:2048
	v_lshl_add_u64 v[52:53], v[82:83], 0, v[36:37]
	s_nop 0
	v_pk_mul_f32 v[48:49], v[72:73], v[84:85] op_sel_hi:[1,0]
	v_pk_mul_f32 v[50:51], v[54:55], v[84:85] op_sel_hi:[1,0]
	v_pk_mul_f32 v[48:49], v[8:9], v[48:49]
	v_pk_mul_f32 v[50:51], v[10:11], v[50:51]
	global_store_dwordx4 v[64:65], v[48:51], off offset:2064
	s_nop 1
	v_pk_mul_f32 v[48:49], v[74:75], v[84:85] op_sel_hi:[1,0]
	v_pk_mul_f32 v[50:51], v[56:57], v[84:85] op_sel_hi:[1,0]
	v_pk_mul_f32 v[48:49], v[20:21], v[48:49]
	v_pk_mul_f32 v[50:51], v[22:23], v[50:51]
	global_store_dwordx4 v[52:53], v[48:51], off
	s_nop 1
	v_pk_mul_f32 v[48:49], v[76:77], v[84:85] op_sel_hi:[1,0]
	v_pk_mul_f32 v[50:51], v[58:59], v[84:85] op_sel_hi:[1,0]
	v_pk_mul_f32 v[48:49], v[16:17], v[48:49]
	v_pk_mul_f32 v[50:51], v[18:19], v[50:51]
	global_store_dwordx4 v[52:53], v[48:51], off offset:16
	v_lshl_add_u64 v[52:53], v[82:83], 0, v[38:39]
	s_nop 0
	v_pk_mul_f32 v[48:49], v[78:79], v[84:85] op_sel_hi:[1,0]
	v_pk_mul_f32 v[50:51], v[60:61], v[84:85] op_sel_hi:[1,0]
	v_pk_mul_f32 v[48:49], v[28:29], v[48:49]
	v_pk_mul_f32 v[50:51], v[30:31], v[50:51]
	global_store_dwordx4 v[52:53], v[48:51], off
	s_nop 1
	v_pk_mul_f32 v[48:49], v[80:81], v[84:85] op_sel_hi:[1,0]
	v_pk_mul_f32 v[50:51], v[62:63], v[84:85] op_sel_hi:[1,0]
	v_pk_mul_f32 v[48:49], v[24:25], v[48:49]
	v_pk_mul_f32 v[50:51], v[26:27], v[50:51]
	global_store_dwordx4 v[52:53], v[48:51], off offset:16
	s_andn2_b64 exec, exec, s[0:1]
	s_cbranch_execnz .LBB0_618
